# P9 hand-written scan plus cooperative L2 prefetch: each of the 16 dv-slice workgroups of a (b,h) touches 1/16 of the K/Q stream 8 pairs ahead
# speedup vs baseline: 1.0088x; 1.0088x over previous
; template <bool RO>
; __device__ __forceinline__ void p9_job(LAS unsigned char* lds, const bf16_t* __restrict__ kap, const bf16_t* __restrict__ vbp, const float* __restrict__ dcp, const bf16_t* __restrict__ qap, bf16_t* __restrict__ op, int wave, int c16, int kq) {
;     ...
;     for (int ct = 0; ct < NCT; ++ct) S[ct] = (f32x4){0.f, 0.f, 0.f, 0.f};
;     bf16x8 ka[PD][2], vb[PD][NCT][2], qa[PD][4]; f32x4 dc[PD];
;     ...
; #pragma unroll
;     for (int u = 0; u < PD; ++u) P9_LOAD(u, u);
; __global__ void __launch_bounds__(512, 2) hybrid_fwd(Args args) {
;     ...
;         for (int jb = blk; jb < 16 * (16 / P9_NCT); jb += G) {
;             constexpr int JPB = 16 / P9_NCT;
;             const int idx = jb >> 3, bh = 2 * (jb & 7) + idx / JPB, dvs = idx % JPB;
;             const int b = bh >> 2, h = bh & 3;
;             const int c16 = lane & 15, kq = lane >> 4;
;             const bf16_t* kap = KDT + (size_t)(b * 4 + h) * 128 * 8192 + wave * 1024 + lane * 8;
;             const bf16_t* vbp = VT + (size_t)(b * 4 + h) * 128 * 16384 + dvs * P9_NCT * 1024 + lane * 8;
;             const float* dcp = DEC + (size_t)(b * 128) * 512 + h * 128 + 16 * wave + 4 * kq;
;             const bf16_t* qap = Qb + (size_t)(b * 4 + h) * 128 * 8192 + (wave & 3) * 2048 + lane * 8;
;             bf16_t* op = Ob + ((size_t)b * SEQ + 16 * (wave & 3) + 4 * kq) * 1024 + h * 256 + dvs * 16 * P9_NCT + c16;
.Lp9_job:
	s_lshr_b32 s11, s9, 3
	s_and_b32 s14, s9, 7
	s_lshl_b32 s14, s14, 1
	s_lshr_b32 s18, s11, 4
	s_add_i32 s14, s14, s18
	s_and_b32 s15, s11, 15
	s_lshr_b32 s16, s14, 2
	s_and_b32 s17, s14, 3
	v_lshlrev_b32_e32 v22, 4, v1
	v_mov_b32_e32 v23, 0
	s_lshl_b32 s18, s14, 21
	s_lshl_b32 s19, s8, 11
	s_add_u32 s18, s18, s19
	s_add_u32 s18, s18, 0x18200000
	s_add_u32 s34, s80, s18
	s_addc_u32 s35, s81, 0
	v_lshl_add_u64 v[12:13], s[34:35], 0, v[22:23]
	s_lshl_b32 s18, s14, 21
	s_lshl_b32 s19, s13, 14
	s_add_u32 s18, s18, s19
	s_lshl_b32 s19, s12, 12
	s_add_u32 s18, s18, s19
	s_add_u32 s18, s18, 0x8200000
	s_add_u32 s34, s80, s18
	s_addc_u32 s35, s81, 0
	v_lshl_add_u64 v[14:15], s[34:35], 0, v[22:23]
	s_lshl_b32 s18, s16, 24
	s_lshl_b32 s19, s13, 17
	s_add_u32 s18, s18, s19
	s_lshl_b32 s19, s12, 15
	s_add_u32 s18, s18, s19
	s_lshl_b32 s19, s17, 9
	s_add_u32 s18, s18, s19
	s_lshl_b32 s19, s15, 5
	s_add_u32 s18, s18, s19
	s_add_u32 s18, s18, 0x1a200000
	s_add_u32 s34, s80, s18
	s_addc_u32 s35, s81, 0
	v_lshlrev_b32_e32 v20, 11, v2
	v_lshl_add_u32 v20, v3, 3, v20
	v_mov_b32_e32 v21, 0
	v_lshl_add_u64 v[20:21], s[34:35], 0, v[20:21]
	s_and_b32 s18, s8, 1
	s_lshl_b32 s18, s18, 10
	s_lshr_b32 s19, s8, 1
	s_lshl_b32 s19, s19, 15
	s_add_u32 s18, s18, s19
	s_lshl_b32 s19, s14, 22
	s_add_u32 s18, s18, s19
	s_lshl_b32 s19, s15, 11
	s_add_u32 s18, s18, s19
	s_add_u32 s18, s18, 0xc200000
	s_lshl_b32 s31, s16, 18
	s_lshl_b32 s19, s17, 9
	s_add_u32 s31, s31, s19
	s_add_u32 s31, s31, 0x3c00000
	s_lshl_b32 s19, s8, 10
	s_add_u32 s19, s19, 0x5000
	s_cmp_lt_u32 s8, 4
	s_cselect_b32 s18, s18, s31
	s_movk_i32 s36, 0x400
	s_movk_i32 s37, 0x1000
	s_cselect_b32 s29, s37, s36
	s_cselect_b32 s22, 0x10000, s37
	s_cselect_b32 s28, s19, 0xd000
	s_cselect_b64 vcc, -1, 0
	s_add_u32 s34, s80, s18
	s_addc_u32 s35, s81, 0
	v_and_b32_e32 v24, 31, v1
	v_lshlrev_b32_e32 v24, 4, v24
	v_lshrrev_b32_e32 v25, 5, v1
	v_lshl_add_u32 v24, v25, 11, v24
	v_cndmask_b32_e32 v16, v24, v22, vcc
	v_mov_b32_e32 v17, 0
	v_lshl_add_u64 v[16:17], s[34:35], 0, v[16:17]
	s_mov_b32 s18, 0x18200000
	s_mov_b32 s19, 0x8200000
	s_cmp_lt_u32 s15, 8
	s_cselect_b32 s18, s18, s19
	s_lshl_b32 s19, s14, 21
	s_add_u32 s18, s18, s19
	s_and_b32 s19, s15, 7
	s_lshl_b32 s19, s19, 12
	s_add_u32 s18, s18, s19
	s_lshl_b32 s19, s8, 10
	s_add_u32 s18, s18, s19
	s_add_u32 s18, s18, 0x40000
	s_add_u32 s34, s80, s18
	s_addc_u32 s35, s81, 0
	v_lshl_add_u64 v[28:29], s[34:35], 0, v[22:23]
	v_mov_b32_e32 v4, 0
	v_mov_b32_e32 v5, 0
	v_mov_b32_e32 v6, 0
	v_mov_b32_e32 v7, 0
	s_cmp_lt_u32 s8, 5
	s_cbranch_scc0 .Lp9_pnd
	s_mul_i32 s11, s29, 0
	s_add_i32 m0, s28, s11
	s_nop 0
	global_load_lds_dwordx4 v[16:17], off
	v_lshl_add_u64 v[16:17], v[16:17], 0, s[22:23]
	s_mul_i32 s11, s29, 1
	s_add_i32 m0, s28, s11
	s_nop 0
	global_load_lds_dwordx4 v[16:17], off
	v_lshl_add_u64 v[16:17], v[16:17], 0, s[22:23]
	s_mul_i32 s11, s29, 2
	s_add_i32 m0, s28, s11
	s_nop 0
	global_load_lds_dwordx4 v[16:17], off
	v_lshl_add_u64 v[16:17], v[16:17], 0, s[22:23]
	s_mul_i32 s11, s29, 3
	s_add_i32 m0, s28, s11
	s_nop 0
	global_load_lds_dwordx4 v[16:17], off
	v_lshl_add_u64 v[16:17], v[16:17], 0, s[22:23]
	s_mul_i32 s11, s29, 4
	s_add_i32 m0, s28, s11
	s_nop 0
	global_load_lds_dwordx4 v[16:17], off
	v_lshl_add_u64 v[16:17], v[16:17], 0, s[22:23]

; template <bool RO>
; __device__ __forceinline__ void p9_job(LAS unsigned char* lds, const bf16_t* __restrict__ kap, const bf16_t* __restrict__ vbp, const float* __restrict__ dcp, const bf16_t* __restrict__ qap, bf16_t* __restrict__ op, int wave, int c16, int kq) {
;     ...
;             const int cn = c + PD < 128 ? c + PD : 127;
;             P9_LOAD(u, cn);
.Lp9_nd0:
	s_cmp_lt_u32 s8, 4
	s_cbranch_scc0 .Lp9_np0
	global_load_dwordx4 v[210:213], v[28:29], off
	v_lshl_add_u64 v[28:29], v[28:29], 0, s[20:21]
